# attention unit epilogue: 16 row-per-lane dwordx2 stores paired by v_permlane32_swap into 8 dwordx4 stores
# baseline (speedup 1.0000x reference)
.LBB0_1778:
	s_andn2_b64 vcc, exec, s[12:13]
	s_waitcnt lgkmcnt(0)
	s_barrier
	s_cbranch_vccnz .LBB0_1762
	v_div_scale_f32 v1, s[38:39], v0, v0, 1.0
	v_rcp_f32_e32 v2, v1
	v_div_scale_f32 v3, vcc, 1.0, v0, 1.0
	s_mov_b32 s37, s5
	v_fma_f32 v4, -v1, v2, 1.0
	v_fmac_f32_e32 v2, v4, v2
	v_mul_f32_e32 v4, v3, v2
	v_fma_f32 v5, -v1, v4, v3
	v_fmac_f32_e32 v4, v5, v2
	v_fma_f32 v1, -v1, v4, v3
	v_div_fmas_f32 v1, v1, v2, v4
	v_div_fixup_f32 v38, v1, v0, 1.0
	ds_read2st64_b32 v[8:9], v184 offset1:1
	ds_read2st64_b32 v[10:11], v184 offset0:2 offset1:3
	ds_read2st64_b32 v[12:13], v184 offset0:4 offset1:5
	ds_read2st64_b32 v[14:15], v184 offset0:6 offset1:7
	ds_read2st64_b32 v[16:17], v184 offset0:8 offset1:9
	ds_read2st64_b32 v[18:19], v184 offset0:10 offset1:11
	ds_read2st64_b32 v[20:21], v184 offset0:12 offset1:13
	ds_read2st64_b32 v[22:23], v184 offset0:14 offset1:15
	ds_read2st64_b32 v[24:25], v184 offset0:16 offset1:17
	ds_read2st64_b32 v[26:27], v184 offset0:18 offset1:19
	ds_read2st64_b32 v[28:29], v184 offset0:20 offset1:21
	ds_read2st64_b32 v[30:31], v184 offset0:22 offset1:23
	ds_read2st64_b32 v[128:129], v184 offset0:24 offset1:25
	ds_read2st64_b32 v[130:131], v184 offset0:26 offset1:27
	ds_read2st64_b32 v[132:133], v184 offset0:28 offset1:29
	ds_read2st64_b32 v[134:135], v184 offset0:30 offset1:31
	ds_read2st64_b32 v[136:137], v184 offset0:32 offset1:33
	ds_read2st64_b32 v[138:139], v184 offset0:34 offset1:35
	ds_read2st64_b32 v[140:141], v184 offset0:36 offset1:37
	ds_read2st64_b32 v[142:143], v184 offset0:38 offset1:39
	ds_read2st64_b32 v[144:145], v184 offset0:40 offset1:41
	ds_read2st64_b32 v[146:147], v184 offset0:42 offset1:43
	ds_read2st64_b32 v[148:149], v184 offset0:44 offset1:45
	ds_read2st64_b32 v[150:151], v184 offset0:46 offset1:47
	ds_read2st64_b32 v[152:153], v184 offset0:56 offset1:57
	ds_read2st64_b32 v[154:155], v184 offset0:58 offset1:59
	ds_read2st64_b32 v[0:1], v184 offset0:60 offset1:61
	ds_read2st64_b32 v[2:3], v184 offset0:62 offset1:63
	ds_read2st64_b32 v[156:157], v184 offset0:48 offset1:49
	ds_read2st64_b32 v[158:159], v184 offset0:50 offset1:51
	ds_read2st64_b32 v[180:181], v184 offset0:52 offset1:53
	ds_read2st64_b32 v[200:201], v184 offset0:54 offset1:55
	s_waitcnt lgkmcnt(14)
	v_pk_fma_f32 v[46:47], v[112:113], v[38:39], v[8:9] op_sel_hi:[1,0,1] neg_lo:[0,0,1] neg_hi:[0,0,1]
	v_pk_fma_f32 v[40:41], v[114:115], v[38:39], v[10:11] op_sel_hi:[1,0,1] neg_lo:[0,0,1] neg_hi:[0,0,1]
	v_pk_mul_f32 v[112:113], v[46:47], v[46:47]
	v_pk_mul_f32 v[114:115], v[40:41], v[40:41]
	v_add_f32_e32 v112, v112, v113
	v_pk_fma_f32 v[52:53], v[116:117], v[38:39], v[12:13] op_sel_hi:[1,0,1] neg_lo:[0,0,1] neg_hi:[0,0,1]
	v_add_f32_e32 v112, v112, v114
	v_pk_mul_f32 v[116:117], v[52:53], v[52:53]
	v_add_f32_e32 v112, v112, v115
	v_pk_fma_f32 v[42:43], v[118:119], v[38:39], v[14:15] op_sel_hi:[1,0,1] neg_lo:[0,0,1] neg_hi:[0,0,1]
	v_add_f32_e32 v112, v112, v116
	v_pk_mul_f32 v[118:119], v[42:43], v[42:43]
	v_add_f32_e32 v112, v112, v117
	v_pk_fma_f32 v[56:57], v[120:121], v[38:39], v[16:17] op_sel_hi:[1,0,1] neg_lo:[0,0,1] neg_hi:[0,0,1]
	v_add_f32_e32 v112, v112, v118
	v_pk_mul_f32 v[120:121], v[56:57], v[56:57]
	v_add_f32_e32 v112, v112, v119
	v_pk_fma_f32 v[48:49], v[122:123], v[38:39], v[18:19] op_sel_hi:[1,0,1] neg_lo:[0,0,1] neg_hi:[0,0,1]
	v_add_f32_e32 v112, v112, v120
	v_pk_mul_f32 v[122:123], v[48:49], v[48:49]
	v_add_f32_e32 v112, v112, v121
	v_pk_fma_f32 v[60:61], v[124:125], v[38:39], v[20:21] op_sel_hi:[1,0,1] neg_lo:[0,0,1] neg_hi:[0,0,1]
	v_add_f32_e32 v112, v112, v122
	v_pk_mul_f32 v[124:125], v[60:61], v[60:61]
	v_add_f32_e32 v112, v112, v123
	v_pk_fma_f32 v[54:55], v[126:127], v[38:39], v[22:23] op_sel_hi:[1,0,1] neg_lo:[0,0,1] neg_hi:[0,0,1]
	v_add_f32_e32 v112, v112, v124
	v_pk_mul_f32 v[126:127], v[54:55], v[54:55]
	v_add_f32_e32 v112, v112, v125
	s_waitcnt lgkmcnt(5)
	v_pk_fma_f32 v[32:33], v[76:77], v[38:39], v[0:1] op_sel_hi:[1,0,1] neg_lo:[0,0,1] neg_hi:[0,0,1]
	v_pk_fma_f32 v[76:77], v[96:97], v[38:39], v[24:25] op_sel_hi:[1,0,1] neg_lo:[0,0,1] neg_hi:[0,0,1]
	v_add_f32_e32 v112, v112, v126
	v_pk_mul_f32 v[202:203], v[76:77], v[76:77]
	v_add_f32_e32 v112, v112, v127
	v_pk_fma_f32 v[58:59], v[98:99], v[38:39], v[26:27] op_sel_hi:[1,0,1] neg_lo:[0,0,1] neg_hi:[0,0,1]
	v_add_f32_e32 v112, v112, v202
	v_lshlrev_b64 v[0:1], 11, v[178:179]
	v_pk_mul_f32 v[178:179], v[58:59], v[58:59]
	v_add_f32_e32 v112, v112, v203
	v_pk_fma_f32 v[96:97], v[100:101], v[38:39], v[28:29] op_sel_hi:[1,0,1] neg_lo:[0,0,1] neg_hi:[0,0,1]
	v_add_f32_e32 v112, v112, v178
	v_pk_mul_f32 v[100:101], v[96:97], v[96:97]
	v_add_f32_e32 v112, v112, v179
	v_pk_fma_f32 v[62:63], v[102:103], v[38:39], v[30:31] op_sel_hi:[1,0,1] neg_lo:[0,0,1] neg_hi:[0,0,1]
	v_add_f32_e32 v100, v112, v100
	v_pk_mul_f32 v[102:103], v[62:63], v[62:63]
	v_add_f32_e32 v100, v100, v101
	v_pk_fma_f32 v[104:105], v[104:105], v[38:39], v[128:129] op_sel_hi:[1,0,1] neg_lo:[0,0,1] neg_hi:[0,0,1]
	v_add_f32_e32 v100, v100, v102
	v_pk_mul_f32 v[128:129], v[104:105], v[104:105]
	v_add_f32_e32 v100, v100, v103
	s_waitcnt lgkmcnt(4)
	v_pk_fma_f32 v[34:35], v[78:79], v[38:39], v[2:3] op_sel_hi:[1,0,1] neg_lo:[0,0,1] neg_hi:[0,0,1]
	v_pk_fma_f32 v[78:79], v[106:107], v[38:39], v[130:131] op_sel_hi:[1,0,1] neg_lo:[0,0,1] neg_hi:[0,0,1]
	v_add_f32_e32 v100, v100, v128
	v_pk_mul_f32 v[106:107], v[78:79], v[78:79]
	v_add_f32_e32 v100, v100, v129
	v_pk_fma_f32 v[108:109], v[108:109], v[38:39], v[132:133] op_sel_hi:[1,0,1] neg_lo:[0,0,1] neg_hi:[0,0,1]
	v_add_f32_e32 v100, v100, v106
	v_pk_mul_f32 v[130:131], v[108:109], v[108:109]
	v_add_f32_e32 v100, v100, v107
	v_pk_fma_f32 v[98:99], v[110:111], v[38:39], v[134:135] op_sel_hi:[1,0,1] neg_lo:[0,0,1] neg_hi:[0,0,1]
	v_add_f32_e32 v100, v100, v130
	v_pk_mul_f32 v[110:111], v[98:99], v[98:99]
	v_add_f32_e32 v100, v100, v131
	v_pk_fma_f32 v[134:135], v[80:81], v[38:39], v[136:137] op_sel_hi:[1,0,1] neg_lo:[0,0,1] neg_hi:[0,0,1]
	v_add_f32_e32 v100, v100, v110
	v_pk_mul_f32 v[80:81], v[134:135], v[134:135]
	v_add_f32_e32 v100, v100, v111
	v_pk_fma_f32 v[132:133], v[82:83], v[38:39], v[138:139] op_sel_hi:[1,0,1] neg_lo:[0,0,1] neg_hi:[0,0,1]
	v_add_f32_e32 v80, v100, v80
	v_pk_mul_f32 v[82:83], v[132:133], v[132:133]
	v_add_f32_e32 v80, v80, v81
	v_pk_fma_f32 v[138:139], v[84:85], v[38:39], v[140:141] op_sel_hi:[1,0,1] neg_lo:[0,0,1] neg_hi:[0,0,1]
	v_add_f32_e32 v80, v80, v82
	v_pk_mul_f32 v[84:85], v[138:139], v[138:139]
	v_add_f32_e32 v80, v80, v83
	v_pk_fma_f32 v[136:137], v[86:87], v[38:39], v[142:143] op_sel_hi:[1,0,1] neg_lo:[0,0,1] neg_hi:[0,0,1]
	v_add_f32_e32 v80, v80, v84
	v_pk_mul_f32 v[86:87], v[136:137], v[136:137]
	v_add_f32_e32 v80, v80, v85
	v_pk_fma_f32 v[142:143], v[88:89], v[38:39], v[144:145] op_sel_hi:[1,0,1] neg_lo:[0,0,1] neg_hi:[0,0,1]
	v_add_f32_e32 v80, v80, v86
	v_pk_mul_f32 v[88:89], v[142:143], v[142:143]
	v_add_f32_e32 v80, v80, v87
	v_pk_fma_f32 v[140:141], v[90:91], v[38:39], v[146:147] op_sel_hi:[1,0,1] neg_lo:[0,0,1] neg_hi:[0,0,1]
	v_add_f32_e32 v80, v80, v88
	v_pk_mul_f32 v[90:91], v[140:141], v[140:141]
	v_add_f32_e32 v80, v80, v89
	v_pk_fma_f32 v[146:147], v[92:93], v[38:39], v[148:149] op_sel_hi:[1,0,1] neg_lo:[0,0,1] neg_hi:[0,0,1]
	v_add_f32_e32 v80, v80, v90
	v_pk_mul_f32 v[92:93], v[146:147], v[146:147]
	v_add_f32_e32 v80, v80, v91
	v_pk_fma_f32 v[144:145], v[94:95], v[38:39], v[150:151] op_sel_hi:[1,0,1] neg_lo:[0,0,1] neg_hi:[0,0,1]
	v_add_f32_e32 v80, v80, v92
	v_pk_mul_f32 v[94:95], v[144:145], v[144:145]
	v_add_f32_e32 v80, v80, v93
	s_waitcnt lgkmcnt(3)
	v_pk_fma_f32 v[150:151], v[64:65], v[38:39], v[156:157] op_sel_hi:[1,0,1] neg_lo:[0,0,1] neg_hi:[0,0,1]
	v_add_f32_e32 v80, v80, v94
	v_pk_mul_f32 v[64:65], v[150:151], v[150:151]
	v_add_f32_e32 v80, v80, v95
	s_waitcnt lgkmcnt(2)
	v_pk_fma_f32 v[148:149], v[66:67], v[38:39], v[158:159] op_sel_hi:[1,0,1] neg_lo:[0,0,1] neg_hi:[0,0,1]
	v_add_f32_e32 v64, v80, v64
	v_pk_mul_f32 v[66:67], v[148:149], v[148:149]
	v_add_f32_e32 v64, v64, v65
	s_waitcnt lgkmcnt(1)
	v_pk_fma_f32 v[158:159], v[68:69], v[38:39], v[180:181] op_sel_hi:[1,0,1] neg_lo:[0,0,1] neg_hi:[0,0,1]
	v_add_f32_e32 v64, v64, v66
	v_pk_mul_f32 v[68:69], v[158:159], v[158:159]
	v_add_f32_e32 v64, v64, v67
	s_waitcnt lgkmcnt(0)
	v_pk_fma_f32 v[156:157], v[70:71], v[38:39], v[200:201] op_sel_hi:[1,0,1] neg_lo:[0,0,1] neg_hi:[0,0,1]
	v_add_f32_e32 v64, v64, v68
	v_pk_mul_f32 v[70:71], v[156:157], v[156:157]
	v_add_f32_e32 v64, v64, v69
	v_pk_fma_f32 v[154:155], v[74:75], v[38:39], v[154:155] op_sel_hi:[1,0,1] neg_lo:[0,0,1] neg_hi:[0,0,1]
	v_pk_fma_f32 v[38:39], v[72:73], v[38:39], v[152:153] op_sel_hi:[1,0,1] neg_lo:[0,0,1] neg_hi:[0,0,1]
	v_add_f32_e32 v64, v64, v70
	v_pk_mul_f32 v[72:73], v[38:39], v[38:39]
	v_add_f32_e32 v64, v64, v71
	v_add_f32_e32 v64, v64, v72
	v_pk_mul_f32 v[74:75], v[154:155], v[154:155]
	v_add_f32_e32 v64, v64, v73
	v_add_f32_e32 v64, v64, v74
	v_pk_mul_f32 v[44:45], v[32:33], v[32:33]
	v_add_f32_e32 v64, v64, v75
	v_add_f32_e32 v44, v64, v44
	v_pk_mul_f32 v[50:51], v[34:35], v[34:35]
	v_add_f32_e32 v44, v44, v45
	v_add_f32_e32 v44, v44, v50
	v_add_f32_e32 v44, v44, v51
	ds_bpermute_b32 v45, v167, v44
	v_lshl_add_u64 v[0:1], s[10:11], 0, v[0:1]
	v_lshl_add_u64 v[0:1], v[0:1], 0, s[36:37]
	v_lshl_add_u64 v[36:37], v[170:171], 1, v[0:1]
	ds_read_b128 v[4:7], v185
	ds_read_b128 v[0:3], v185 offset:32
	s_waitcnt lgkmcnt(2)
	v_add_f32_e32 v44, v44, v45
	v_fmamk_f32 v44, v44, 0x3c000000, v198
	v_mul_f32_e32 v45, 0x4b800000, v44
	v_cmp_gt_f32_e32 vcc, s51, v44
	ds_read_b128 v[12:15], v185 offset:64
	ds_read_b128 v[8:11], v185 offset:96
	v_cndmask_b32_e32 v44, v44, v45, vcc
	v_rsq_f32_e32 v44, v44
	ds_read_b128 v[20:23], v185 offset:128
	ds_read_b128 v[16:19], v185 offset:160
	ds_read_b128 v[28:31], v185 offset:192
	ds_read_b128 v[24:27], v185 offset:224
	ds_read_b128 v[64:67], v185 offset:256
	ds_read_b128 v[68:71], v185 offset:288
	ds_read_b128 v[72:75], v185 offset:320
	ds_read_b128 v[80:83], v185 offset:352
	v_mul_f32_e32 v45, 0x45800000, v44
	v_cndmask_b32_e32 v44, v44, v45, vcc
	v_mul_f32_e32 v44, 0x3f24fd5c, v44
	v_pk_mul_f32 v[46:47], v[46:47], v[44:45] op_sel_hi:[1,0]
	v_pk_mul_f32 v[40:41], v[40:41], v[44:45] op_sel_hi:[1,0]
	s_waitcnt lgkmcnt(11)
	v_pk_mul_f32 v[4:5], v[4:5], v[46:47]
	v_pk_mul_f32 v[6:7], v[6:7], v[40:41]
	v_cvt_pk_bf16_f32 v228, v4, v5
	v_mbcnt_lo_u32_b32 v238, -1, 0
	v_mbcnt_hi_u32_b32 v238, -1, v238
	v_and_b32_e32 v238, 32, v238
	v_lshrrev_b32_e32 v238, 2, v238
	v_mov_b32_e32 v239, 0
	v_lshl_add_u64 v[236:237], v[36:37], 0, v[238:239]
	v_cvt_pk_bf16_f32 v229, v6, v7
	ds_read_b128 v[84:87], v185 offset:384
	ds_read_b128 v[88:91], v185 offset:416
	ds_read_b128 v[92:95], v185 offset:448
	v_pk_mul_f32 v[4:5], v[52:53], v[44:45] op_sel_hi:[1,0]
	v_pk_mul_f32 v[6:7], v[154:155], v[44:45] op_sel_hi:[1,0]
	s_waitcnt lgkmcnt(13)
	v_pk_mul_f32 v[0:1], v[0:1], v[4:5]
	v_pk_mul_f32 v[4:5], v[42:43], v[44:45] op_sel_hi:[1,0]
	v_cvt_pk_bf16_f32 v230, v0, v1
	v_pk_mul_f32 v[2:3], v[2:3], v[4:5]
	v_pk_mul_f32 v[4:5], v[38:39], v[44:45] op_sel_hi:[1,0]
	v_cvt_pk_bf16_f32 v231, v2, v3
	s_nop 1
	v_permlane32_swap_b32_e32 v228, v230
	v_permlane32_swap_b32_e32 v229, v231
	global_store_dwordx4 v[236:237], v[228:231], off
	v_pk_mul_f32 v[0:1], v[56:57], v[44:45] op_sel_hi:[1,0]
	v_pk_mul_f32 v[2:3], v[48:49], v[44:45] op_sel_hi:[1,0]
	s_waitcnt lgkmcnt(12)
	v_pk_mul_f32 v[0:1], v[12:13], v[0:1]
	v_pk_mul_f32 v[2:3], v[14:15], v[2:3]
	v_cvt_pk_bf16_f32 v232, v0, v1
	v_cvt_pk_bf16_f32 v233, v2, v3
	v_pk_mul_f32 v[0:1], v[60:61], v[44:45] op_sel_hi:[1,0]
	v_pk_mul_f32 v[2:3], v[54:55], v[44:45] op_sel_hi:[1,0]
	s_waitcnt lgkmcnt(11)
	v_pk_mul_f32 v[0:1], v[8:9], v[0:1]
	v_pk_mul_f32 v[2:3], v[10:11], v[2:3]
	v_cvt_pk_bf16_f32 v234, v0, v1
	v_cvt_pk_bf16_f32 v235, v2, v3
	s_nop 1
	v_permlane32_swap_b32_e32 v232, v234
	v_permlane32_swap_b32_e32 v233, v235
	global_store_dwordx4 v[236:237], v[232:235], off offset:32
	v_pk_mul_f32 v[0:1], v[76:77], v[44:45] op_sel_hi:[1,0]
	v_pk_mul_f32 v[2:3], v[58:59], v[44:45] op_sel_hi:[1,0]
	s_waitcnt lgkmcnt(10)
	v_pk_mul_f32 v[0:1], v[20:21], v[0:1]
	v_pk_mul_f32 v[2:3], v[22:23], v[2:3]
	v_cvt_pk_bf16_f32 v228, v0, v1
	v_cvt_pk_bf16_f32 v229, v2, v3
	v_pk_mul_f32 v[0:1], v[96:97], v[44:45] op_sel_hi:[1,0]
	v_pk_mul_f32 v[2:3], v[62:63], v[44:45] op_sel_hi:[1,0]
	s_waitcnt lgkmcnt(9)
	v_pk_mul_f32 v[0:1], v[16:17], v[0:1]
	v_pk_mul_f32 v[2:3], v[18:19], v[2:3]
	v_cvt_pk_bf16_f32 v230, v0, v1
	v_cvt_pk_bf16_f32 v231, v2, v3
	s_nop 1
	v_permlane32_swap_b32_e32 v228, v230
	v_permlane32_swap_b32_e32 v229, v231
	global_store_dwordx4 v[236:237], v[228:231], off offset:64
	v_pk_mul_f32 v[0:1], v[104:105], v[44:45] op_sel_hi:[1,0]
	v_pk_mul_f32 v[2:3], v[78:79], v[44:45] op_sel_hi:[1,0]
	s_waitcnt lgkmcnt(8)
	v_pk_mul_f32 v[0:1], v[0:1], v[28:29]
	v_pk_mul_f32 v[2:3], v[2:3], v[30:31]
	v_cvt_pk_bf16_f32 v232, v0, v1
	v_cvt_pk_bf16_f32 v233, v2, v3
	v_pk_mul_f32 v[0:1], v[108:109], v[44:45] op_sel_hi:[1,0]
	v_pk_mul_f32 v[2:3], v[98:99], v[44:45] op_sel_hi:[1,0]
	s_waitcnt lgkmcnt(7)
	v_pk_mul_f32 v[0:1], v[0:1], v[24:25]
	v_pk_mul_f32 v[2:3], v[2:3], v[26:27]
	v_cvt_pk_bf16_f32 v234, v0, v1
	v_cvt_pk_bf16_f32 v235, v2, v3
	s_nop 1
	v_permlane32_swap_b32_e32 v232, v234
	v_permlane32_swap_b32_e32 v233, v235
	global_store_dwordx4 v[236:237], v[232:235], off offset:96
	v_pk_mul_f32 v[0:1], v[134:135], v[44:45] op_sel_hi:[1,0]
	v_pk_mul_f32 v[2:3], v[132:133], v[44:45] op_sel_hi:[1,0]
	s_waitcnt lgkmcnt(6)
	v_pk_mul_f32 v[0:1], v[0:1], v[64:65]
	v_pk_mul_f32 v[2:3], v[2:3], v[66:67]
	v_cvt_pk_bf16_f32 v228, v0, v1
	v_cvt_pk_bf16_f32 v229, v2, v3
	v_pk_mul_f32 v[0:1], v[138:139], v[44:45] op_sel_hi:[1,0]
	v_pk_mul_f32 v[2:3], v[136:137], v[44:45] op_sel_hi:[1,0]
	s_waitcnt lgkmcnt(5)
	v_pk_mul_f32 v[0:1], v[0:1], v[68:69]
	v_pk_mul_f32 v[2:3], v[2:3], v[70:71]
	v_cvt_pk_bf16_f32 v230, v0, v1
	v_cvt_pk_bf16_f32 v231, v2, v3
	s_nop 1
	v_permlane32_swap_b32_e32 v228, v230
	v_permlane32_swap_b32_e32 v229, v231
	global_store_dwordx4 v[236:237], v[228:231], off offset:128
	v_pk_mul_f32 v[0:1], v[142:143], v[44:45] op_sel_hi:[1,0]
	v_pk_mul_f32 v[2:3], v[140:141], v[44:45] op_sel_hi:[1,0]
	s_waitcnt lgkmcnt(4)
	v_pk_mul_f32 v[0:1], v[0:1], v[72:73]
	v_pk_mul_f32 v[2:3], v[2:3], v[74:75]
	v_cvt_pk_bf16_f32 v232, v0, v1
	v_cvt_pk_bf16_f32 v233, v2, v3
	v_pk_mul_f32 v[0:1], v[146:147], v[44:45] op_sel_hi:[1,0]
	v_pk_mul_f32 v[2:3], v[144:145], v[44:45] op_sel_hi:[1,0]
	s_waitcnt lgkmcnt(3)
	v_pk_mul_f32 v[0:1], v[0:1], v[80:81]
	v_pk_mul_f32 v[2:3], v[2:3], v[82:83]
	v_cvt_pk_bf16_f32 v234, v0, v1
	v_cvt_pk_bf16_f32 v235, v2, v3
	s_nop 1
	v_permlane32_swap_b32_e32 v232, v234
	v_permlane32_swap_b32_e32 v233, v235
	global_store_dwordx4 v[236:237], v[232:235], off offset:160
	v_pk_mul_f32 v[0:1], v[150:151], v[44:45] op_sel_hi:[1,0]
	v_pk_mul_f32 v[2:3], v[148:149], v[44:45] op_sel_hi:[1,0]
	s_waitcnt lgkmcnt(2)
	v_pk_mul_f32 v[0:1], v[0:1], v[84:85]
	v_pk_mul_f32 v[2:3], v[2:3], v[86:87]
	v_cvt_pk_bf16_f32 v228, v0, v1
	v_cvt_pk_bf16_f32 v229, v2, v3
	v_pk_mul_f32 v[0:1], v[158:159], v[44:45] op_sel_hi:[1,0]
	v_pk_mul_f32 v[2:3], v[156:157], v[44:45] op_sel_hi:[1,0]
	s_waitcnt lgkmcnt(1)
	v_pk_mul_f32 v[0:1], v[0:1], v[88:89]
	v_pk_mul_f32 v[2:3], v[2:3], v[90:91]
	v_cvt_pk_bf16_f32 v230, v0, v1
	v_cvt_pk_bf16_f32 v231, v2, v3
	s_nop 1
	v_permlane32_swap_b32_e32 v228, v230
	v_permlane32_swap_b32_e32 v229, v231
	global_store_dwordx4 v[236:237], v[228:231], off offset:192
	ds_read_b128 v[0:3], v185 offset:480
	s_waitcnt lgkmcnt(1)
	v_pk_mul_f32 v[4:5], v[4:5], v[92:93]
	v_pk_mul_f32 v[6:7], v[6:7], v[94:95]
	v_cvt_pk_bf16_f32 v232, v4, v5
	v_cvt_pk_bf16_f32 v233, v6, v7
	v_pk_mul_f32 v[4:5], v[32:33], v[44:45] op_sel_hi:[1,0]
	s_waitcnt lgkmcnt(0)
	v_pk_mul_f32 v[0:1], v[4:5], v[0:1]
	v_pk_mul_f32 v[4:5], v[34:35], v[44:45] op_sel_hi:[1,0]
	v_cvt_pk_bf16_f32 v234, v0, v1
	v_pk_mul_f32 v[2:3], v[4:5], v[2:3]
	s_nop 0
	v_cvt_pk_bf16_f32 v235, v2, v3
	s_nop 1
	v_permlane32_swap_b32_e32 v232, v234
	v_permlane32_swap_b32_e32 v233, v235
	global_store_dwordx4 v[236:237], v[232:235], off offset:224
	s_branch .LBB0_1762
